# RWKV chunk loop: stage fragments read in one batch; old T fragment read together with the operands in the power stages
# baseline (speedup 1.0000x reference)
; #define LAS __attribute__((address_space(3)))
; #define LBAR() do { asm volatile("s_waitcnt lgkmcnt(0)" ::: "memory"); __builtin_amdgcn_s_barrier(); asm volatile("" ::: "memory"); } while (0)
; __device__ void rwkv_chunk_phase(const Params& p, int l, LAS unsigned char* lds) {
;     ...
;             {   const f32x4 lgl = *(const LAS f32x4*)(lgp_s + tok * 64 + j0), tot = *(const LAS f32x4*)(tot_s + j0);
;                 f32x4 ctv, btv, ktv, rtv, bgv, kgv;
; #pragma unroll
;                 for (int j = 0; j < 4; ++j) {
;                     const float lg = lgl[j], lgp = lg - lw4[j];
;                     const float einv = __expf(-lg), eL = __expf(tot[j] - lg);
;                     ctv[j] = kk4[j] * __expf(lgp); btv[j] = b4[j] * einv; ktv[j] = kd4[j] * einv; rtv[j] = r4[j] * __expf(dir ? lgp : lg);
;                     bgv[j] = b4[j] * eL; kgv[j] = kd4[j] * eL;
;                 }
;                 st_bf4(Ct + tok * 72 + j0, ctv); st_bf4(Bt + tok * 72 + j0, btv); st_bf4(Kt + tok * 72 + j0, ktv); st_bf4(Rt + tok * 72 + j0, rtv);
;                 st_bf4(BgT + tok * 72 + j0, bgv); st_bf4(KgT + tok * 72 + j0, kgv); st_bf4(VtT + tok * 72 + j0, v4);
;             }
;             }
;             LBAR();
; #pragma unroll
;             for (int i = 0; i < 2; ++i) { const int id = wid + 8 * i, pr = id >> 2, rt = (id >> 1) & 1, ct = id & 1;
;                 const LAS bf16_t* X = (pr < 2) ? Ct : Rt; const LAS bf16_t* Yo = (pr == 0 || pr == 3) ? Bt : Kt;
;                 const f32x4 z4 = {0.f, 0.f, 0.f, 0.f};
;                 f32x4 acc = mm_nt<2>(X, 72, rt * 16, Yo, 72, ct * 16, r16, quad, z4);
;                 const int col = ct * 16 + r16, rb = rt * 16 + quad * 4;
;                 const bool strictm = (pr < 2) || dir;
; #pragma unroll
;                 for (int j = 0; j < 4; ++j) { const int row = rb + j; const bool keep = strictm ? (row > col) : (row >= col); acc[j] = keep ? acc[j] : 0.f; }
;                 if (pr == 0) { f32x4 t0v;
; #pragma unroll
;                     for (int j = 0; j < 4; ++j) t0v[j] = ((rb + j) == col ? 1.0f : 0.0f) - acc[j];
;                     const f32x4 na = -acc; st_bf4(PTq[0] + col * 40 + rb, na); st_bf4(Tq[0] + col * 40 + rb, t0v); }
;                 else { LAS bf16_t* D = (pr == 1) ? QTT : ((pr == 2) ? MKT : MBT); st_bf4(D + col * 40 + rb, acc); } }
.LBB0_331:
	v_add_f32_e32 v0, v51, v218
	v_add_f32_e32 v0, 0x2b8cbccc, v0
	s_waitcnt lgkmcnt(0)
	s_barrier
	ds_read_b128 v[44:47], v94 offset:55808
	v_rsq_f32_e32 v0, v0
	s_nop 0
	v_pk_mul_f32 v[2:3], v[70:71], v[0:1] op_sel_hi:[1,0]
	v_pk_mul_f32 v[138:139], v[68:69], v[0:1] op_sel_hi:[1,0]
	ds_read_b128 v[68:71], v96 offset:18944
	s_waitcnt lgkmcnt(0)
	v_sub_f32_e32 v0, v44, v36
	v_mul_f32_e32 v36, 0xbfb8aa3b, v44
	v_exp_f32_e32 v36, v36
	v_pk_mul_f32 v[64:65], v[64:65], v[2:3]
	v_sub_f32_e32 v51, v68, v44
	v_mul_f32_e32 v51, 0x3fb8aa3b, v51
	v_exp_f32_e32 v68, v51
	v_mul_f32_e32 v51, 0x3fb8aa3b, v0
	v_cndmask_b32_e64 v0, v44, v0, s[4:5]
	v_exp_f32_e32 v218, v51
	v_mul_f32_e32 v0, 0x3fb8aa3b, v0
	v_sub_f32_e32 v51, v69, v45
	v_exp_f32_e32 v44, v0
	v_sub_f32_e32 v0, v45, v37
	v_mul_f32_e32 v51, 0x3fb8aa3b, v51
	v_exp_f32_e32 v69, v51
	v_mul_f32_e32 v51, 0x3fb8aa3b, v0
	v_cndmask_b32_e64 v0, v45, v0, s[4:5]
	v_mul_f32_e32 v37, 0xbfb8aa3b, v45
	v_mul_f32_e32 v0, 0x3fb8aa3b, v0
	v_exp_f32_e32 v37, v37
	v_exp_f32_e32 v219, v51
	v_exp_f32_e32 v45, v0
	v_sub_f32_e32 v51, v70, v46
	v_sub_f32_e32 v0, v46, v38
	v_mul_f32_e32 v51, 0x3fb8aa3b, v51
	v_pk_mul_f32 v[2:3], v[2:3], v[218:219]
	v_pk_mul_f32 v[218:219], v[64:65], v[36:37]
	v_pk_mul_f32 v[40:41], v[40:41], v[44:45]
	v_pk_mul_f32 v[44:45], v[64:65], v[68:69]
	v_exp_f32_e32 v64, v51
	v_mul_f32_e32 v51, 0x3fb8aa3b, v0
	v_cndmask_b32_e64 v0, v46, v0, s[4:5]
	v_pk_mul_f32 v[36:37], v[62:63], v[36:37]
	v_pk_mul_f32 v[62:63], v[62:63], v[68:69]
	v_exp_f32_e32 v68, v51
	v_mul_f32_e32 v0, 0x3fb8aa3b, v0
	v_sub_f32_e32 v51, v71, v47
	v_mul_f32_e32 v38, 0xbfb8aa3b, v46
	v_exp_f32_e32 v46, v0
	v_sub_f32_e32 v0, v47, v39
	v_mul_f32_e32 v51, 0x3fb8aa3b, v51
	v_exp_f32_e32 v65, v51
	v_mul_f32_e32 v51, 0x3fb8aa3b, v0
	v_mul_f32_e32 v39, 0xbfb8aa3b, v47
	v_exp_f32_e32 v69, v51
	v_exp_f32_e32 v38, v38
	v_exp_f32_e32 v39, v39
	v_cndmask_b32_e64 v0, v47, v0, s[4:5]
	v_mul_f32_e32 v0, 0x3fb8aa3b, v0
	v_exp_f32_e32 v47, v0
	v_pk_mul_f32 v[66:67], v[66:67], v[138:139]
	v_pk_mul_f32 v[68:69], v[138:139], v[68:69]
	v_pk_mul_f32 v[70:71], v[66:67], v[38:39]
	v_cvt_pk_bf16_f32 v2, v2, v3
	v_cvt_pk_bf16_f32 v3, v68, v69
	v_pk_mul_f32 v[38:39], v[60:61], v[38:39]
	ds_write_b64 v101, v[2:3] offset:65024
	v_cvt_pk_bf16_f32 v2, v218, v219
	v_cvt_pk_bf16_f32 v3, v70, v71
	v_pk_mul_f32 v[42:43], v[42:43], v[46:47]
	ds_write_b64 v102, v[2:3]
	v_cvt_pk_bf16_f32 v2, v36, v37
	v_cvt_pk_bf16_f32 v3, v38, v39
	v_pk_mul_f32 v[46:47], v[66:67], v[64:65]
	ds_write_b64 v103, v[2:3]
	v_cvt_pk_bf16_f32 v2, v40, v41
	v_cvt_pk_bf16_f32 v3, v42, v43
	v_pk_mul_f32 v[60:61], v[60:61], v[64:65]
	ds_write_b64 v104, v[2:3]
	v_cvt_pk_bf16_f32 v2, v44, v45
	v_cvt_pk_bf16_f32 v3, v46, v47
	ds_write_b64 v105, v[2:3]
	v_cvt_pk_bf16_f32 v2, v62, v63
	v_cvt_pk_bf16_f32 v3, v60, v61
	ds_write_b64 v106, v[2:3]
	v_cvt_pk_bf16_f32 v2, v32, v33
	v_cvt_pk_bf16_f32 v3, v34, v35
	ds_write_b64 v107, v[2:3]
	s_waitcnt lgkmcnt(0)
	s_barrier
	ds_read_b128 v[32:35], v155
	ds_read_b128 v[36:39], v155 offset:64
	ds_read_b128 v[40:43], v156
	ds_read_b128 v[44:47], v156 offset:64
	ds_read_b128 v[230:233], v163
	ds_read_b128 v[234:237], v164
	ds_read_b128 v[238:241], v163 offset:64
	ds_read_b128 v[242:245], v164 offset:64
	s_waitcnt lgkmcnt(0)
	v_mfma_f32_16x16x32_bf16 v[32:35], v[32:35], v[40:43], 0
	v_mfma_f32_16x16x32_bf16 v[32:35], v[36:39], v[44:47], v[32:35]
	s_nop 7
	v_cndmask_b32_e64 v0, 0, v32, s[8:9]
	v_cndmask_b32_e64 v3, v33, 0, s[10:11]
	v_cndmask_b32_e64 v2, 0, v34, s[12:13]
	v_cndmask_b32_e64 v32, 0, v35, s[14:15]
	s_and_saveexec_b64 s[24:25], s[72:73]
	s_xor_b64 s[24:25], exec, s[24:25]
	v_cvt_pk_bf16_f32 v34, v0, v3
	v_cvt_pk_bf16_f32 v35, v2, v32
	ds_write_b64 v158, v[34:35]
	s_andn2_saveexec_b64 s[24:25], s[24:25]
	s_cbranch_execz .LBB0_335
	v_sub_f32_e32 v33, v159, v0
	v_sub_f32_e32 v35, v161, v2
	v_sub_f32_e32 v36, v162, v32
	v_xor_b32_e32 v32, 0x80000000, v32
	v_xor_b32_e32 v37, 0x80000000, v2
	v_xor_b32_e32 v2, 0x80000000, v3
	v_xor_b32_e32 v0, 0x80000000, v0
	v_sub_f32_e32 v34, v160, v3
	v_cvt_pk_bf16_f32 v2, v0, v2
	v_cvt_pk_bf16_f32 v3, v37, v32
	ds_write_b64 v111, v[2:3]
	v_cvt_pk_bf16_f32 v2, v33, v34
	v_cvt_pk_bf16_f32 v3, v35, v36
	ds_write_b64 v112, v[2:3]
; __device__ void rwkv_chunk_phase(const Params& p, int l, LAS unsigned char* lds) {
;     ...
;             for (int i = 0; i < 2; ++i) { const int id = wid + 8 * i, pr = id >> 2, rt = (id >> 1) & 1, ct = id & 1;
;                 const LAS bf16_t* X = (pr < 2) ? Ct : Rt; const LAS bf16_t* Yo = (pr == 0 || pr == 3) ? Bt : Kt;
;                 const f32x4 z4 = {0.f, 0.f, 0.f, 0.f};
;                 f32x4 acc = mm_nt<2>(X, 72, rt * 16, Yo, 72, ct * 16, r16, quad, z4);
;                 const int col = ct * 16 + r16, rb = rt * 16 + quad * 4;
;                 const bool strictm = (pr < 2) || dir;
; #pragma unroll
;                 for (int j = 0; j < 4; ++j) { const int row = rb + j; const bool keep = strictm ? (row > col) : (row >= col); acc[j] = keep ? acc[j] : 0.f; }
;                 if (pr == 0) { f32x4 t0v;
; #pragma unroll
;                     for (int j = 0; j < 4; ++j) t0v[j] = ((rb + j) == col ? 1.0f : 0.0f) - acc[j];
;                     const f32x4 na = -acc; st_bf4(PTq[0] + col * 40 + rb, na); st_bf4(Tq[0] + col * 40 + rb, t0v); }
;                 else { LAS bf16_t* D = (pr == 1) ? QTT : ((pr == 2) ? MKT : MBT); st_bf4(D + col * 40 + rb, acc); } }
;             LBAR();
;             {   const int rt = wid >> 2, ct = wid & 3; const f32x4 z4 = {0.f, 0.f, 0.f, 0.f};
;                 f32x4 acc = mm_nt<2>(Ct, 72, rt * 16, S0b[cur], 72, ct * 16, r16, quad, z4);
;                 acc = __builtin_amdgcn_mfma_f32_16x16x32_bf16(trfrag(QTT, 40, 0, rt * 16, lane), trfrag(VtT, 72, 0, ct * 16, lane), acc, 0, 0, 0);
;                 st_bf4(CtT + (ct * 16 + r16) * 40 + rt * 16 + quad * 4, acc); }
;             if (wid < 4) { const int rt = wid >> 1, ct = wid & 1; const f32x4 z4 = {0.f, 0.f, 0.f, 0.f};
;                 const f32x4 acc = __builtin_amdgcn_mfma_f32_16x16x32_bf16(trfrag(PTq[0], 40, 0, rt * 16, lane), *(const LAS bf16x8*)(PTq[0] + (ct * 16 + r16) * 40 + quad * 8), z4, 0, 0, 0);
;                 st_bf4(PTq[1] + (ct * 16 + r16) * 40 + rt * 16 + quad * 4, acc); }
;             LBAR();
; #pragma unroll
;             for (int st = 0; st < 3; ++st) { const int pi = (st & 1) ? 0 : 1, ti = st & 1;
;                 const int rt = (wid >> 1) & 1, ct = wid & 1; const f32x4 z4 = {0.f, 0.f, 0.f, 0.f};
;                 const int col = ct * 16 + r16, rb = rt * 16 + quad * 4;
;                 const bf16x8 yb = *(const LAS bf16x8*)(PTq[pi] + col * 40 + quad * 8);
.LBB0_335:
	s_or_b64 exec, exec, s[24:25]
	s_nop 3
	v_mfma_f32_16x16x32_bf16 v[32:35], v[230:233], v[234:237], 0
	v_mfma_f32_16x16x32_bf16 v[32:35], v[238:241], v[242:245], v[32:35]
	s_nop 7
	v_cndmask_b32_e64 v0, 0, v32, s[16:17]
	v_cndmask_b32_e64 v3, v33, 0, s[18:19]
	v_cndmask_b32_e64 v2, 0, v34, s[20:21]
	v_cndmask_b32_e64 v32, 0, v35, s[22:23]
	s_and_saveexec_b64 s[24:25], s[88:89]
	s_xor_b64 s[24:25], exec, s[24:25]
	v_cvt_pk_bf16_f32 v34, v0, v3
	v_cvt_pk_bf16_f32 v35, v2, v32
	ds_write_b64 v165, v[34:35]
	s_andn2_saveexec_b64 s[24:25], s[24:25]
	s_cbranch_execz .LBB0_339
	v_sub_f32_e32 v33, v159, v0
	v_sub_f32_e32 v35, v161, v2
	v_sub_f32_e32 v36, v162, v32
	v_xor_b32_e32 v32, 0x80000000, v32
	v_xor_b32_e32 v37, 0x80000000, v2
	v_xor_b32_e32 v2, 0x80000000, v3
	v_xor_b32_e32 v0, 0x80000000, v0
	v_sub_f32_e32 v34, v160, v3
	v_cvt_pk_bf16_f32 v2, v0, v2
	v_cvt_pk_bf16_f32 v3, v37, v32
	ds_write_b64 v111, v[2:3]
	v_cvt_pk_bf16_f32 v2, v33, v34
	v_cvt_pk_bf16_f32 v3, v35, v36
	ds_write_b64 v112, v[2:3]
.LBB0_339:
	s_or_b64 exec, exec, s[24:25]
	s_cmp_eq_u32 s64, 1
	s_cselect_b32 s24, s50, 0x9200
	s_add_i32 s24, s24, 0
	s_waitcnt lgkmcnt(0)
	s_barrier
	v_add_u32_e32 v0, s24, v114
	v_lshl_add_u32 v2, v88, 1, v0
	ds_read_b128 v[32:35], v113 offset:65024
	ds_read_b128 v[36:39], v2
	ds_read_b128 v[40:43], v113 offset:65088
	ds_read_b128 v[230:233], v2 offset:64
	ds_read_b64_tr_b16 v[234:235], v115
	ds_read_b64_tr_b16 v[236:237], v115 offset:320
	ds_read_b64_tr_b16 v[238:239], v116
	ds_read_b64_tr_b16 v[240:241], v116 offset:576
	v_add_u32_e32 v3, v110, v90
	s_waitcnt lgkmcnt(0)
	v_mfma_f32_16x16x32_bf16 v[32:35], v[32:35], v[36:39], 0
	v_mfma_f32_16x16x32_bf16 v[32:35], v[40:43], v[230:233], v[32:35]
	v_mfma_f32_16x16x32_bf16 v[32:35], v[234:237], v[238:241], v[32:35]
	s_nop 7
	v_cvt_pk_bf16_f32 v32, v32, v33
	v_cvt_pk_bf16_f32 v33, v34, v35
	ds_write_b64 v117, v[32:33]
	s_and_saveexec_b64 s[24:25], s[66:67]
	s_cbranch_execz .LBB0_341
	ds_read_b64_tr_b16 v[32:33], v118
	ds_read_b64_tr_b16 v[34:35], v118 offset:320
	ds_read_b128 v[36:39], v3
	s_waitcnt lgkmcnt(0)
	v_mfma_f32_16x16x32_bf16 v[32:35], v[32:35], v[36:39], 0
	s_nop 7
	v_cvt_pk_bf16_f32 v32, v32, v33
	v_cvt_pk_bf16_f32 v33, v34, v35
	ds_write_b64 v120, v[32:33]
.LBB0_341:
	s_or_b64 exec, exec, s[24:25]
	s_waitcnt lgkmcnt(0)
	s_barrier
	v_add_u32_e32 v36, v119, v90
	ds_read_b128 v[32:35], v36
	s_and_saveexec_b64 s[24:25], s[68:69]
	s_xor_b64 s[24:25], exec, s[24:25]
	s_cbranch_execz .LBB0_343
	ds_read_b64_tr_b16 v[38:39], v166
	ds_read_b64_tr_b16 v[40:41], v166 offset:320
	ds_read_b64 v[230:231], v167
	s_waitcnt lgkmcnt(0)
	v_mfma_f32_16x16x32_bf16 v[32:35], v[38:41], v[32:35], 0
	v_lshlrev_b32_e32 v40, 16, v230
	v_and_b32_e32 v41, 0xffff0000, v230
	v_lshlrev_b32_e32 v38, 16, v231
	v_and_b32_e32 v39, 0xffff0000, v231
	s_nop 3
	v_pk_add_f32 v[32:33], v[32:33], v[40:41]
	v_pk_add_f32 v[34:35], v[34:35], v[38:39]
	v_cvt_pk_bf16_f32 v32, v32, v33
	v_cvt_pk_bf16_f32 v33, v34, v35
	ds_write_b64 v179, v[32:33]

; #define LAS __attribute__((address_space(3)))
; __device__ __forceinline__ float bf_lo(unsigned w) { return __uint_as_float(w << 16); }
; __device__ __forceinline__ float bf_hi(unsigned w) { return __uint_as_float(w & 0xffff0000u); }
; __device__ __forceinline__ void st_bf4(LAS bf16_t* p, const f32x4 v) { u32x2 w; w.x = cvt_pk_bf16(v[0], v[1]); w.y = cvt_pk_bf16(v[2], v[3]); *(LAS u32x2*)p = w; }
; __device__ void rwkv_chunk_phase(const Params& p, int l, LAS unsigned char* lds) {
;     ...
;             for (int st = 0; st < 3; ++st) { const int pi = (st & 1) ? 0 : 1, ti = st & 1;
;                 const int rt = (wid >> 1) & 1, ct = wid & 1; const f32x4 z4 = {0.f, 0.f, 0.f, 0.f};
;                 const int col = ct * 16 + r16, rb = rt * 16 + quad * 4;
;                 const bf16x8 yb = *(const LAS bf16x8*)(PTq[pi] + col * 40 + quad * 8);
;                 if (wid < 4) { const f32x4 acc = __builtin_amdgcn_mfma_f32_16x16x32_bf16(trfrag(PTq[pi], 40, 0, rt * 16, lane), yb, z4, 0, 0, 0);
;                     st_bf4(PTq[pi ^ 1] + col * 40 + rb, acc); }
;                 else { f32x4 acc = __builtin_amdgcn_mfma_f32_16x16x32_bf16(trfrag(Tq[ti], 40, 0, rt * 16, lane), yb, z4, 0, 0, 0);
;                     const u32x2 tw = *(const LAS u32x2*)(Tq[ti] + col * 40 + rb);
;                     acc[0] += bf_lo(tw.x); acc[1] += bf_hi(tw.x); acc[2] += bf_lo(tw.y); acc[3] += bf_hi(tw.y);
;                     st_bf4(Tq[ti ^ 1] + col * 40 + rb, acc); }
.LBB0_345:
	s_or_b64 exec, exec, s[24:25]
	s_waitcnt lgkmcnt(0)
	s_barrier
	s_waitcnt lgkmcnt(0)
	ds_read_b128 v[32:35], v3
	s_and_saveexec_b64 s[24:25], s[68:69]
	s_xor_b64 s[24:25], exec, s[24:25]
	s_cbranch_execz .LBB0_347
	ds_read_b64_tr_b16 v[38:39], v182
	ds_read_b64_tr_b16 v[40:41], v182 offset:320
	ds_read_b64 v[230:231], v179
	s_waitcnt lgkmcnt(0)
	v_mfma_f32_16x16x32_bf16 v[32:35], v[38:41], v[32:35], 0
	v_lshlrev_b32_e32 v40, 16, v230
	v_and_b32_e32 v41, 0xffff0000, v230
	v_lshlrev_b32_e32 v38, 16, v231
	v_and_b32_e32 v39, 0xffff0000, v231
	s_nop 3
	v_pk_add_f32 v[32:33], v[32:33], v[40:41]
	v_pk_add_f32 v[34:35], v[34:35], v[38:39]
	v_cvt_pk_bf16_f32 v32, v32, v33
	v_cvt_pk_bf16_f32 v33, v34, v35
	ds_write_b64 v167, v[32:33]

; #define LAS __attribute__((address_space(3)))
; __device__ __forceinline__ float bf_lo(unsigned w) { return __uint_as_float(w << 16); }
; __device__ __forceinline__ float bf_hi(unsigned w) { return __uint_as_float(w & 0xffff0000u); }
; __device__ __forceinline__ void st_bf4(LAS bf16_t* p, const f32x4 v) { u32x2 w; w.x = cvt_pk_bf16(v[0], v[1]); w.y = cvt_pk_bf16(v[2], v[3]); *(LAS u32x2*)p = w; }
; __device__ void rwkv_chunk_phase(const Params& p, int l, LAS unsigned char* lds) {
;     ...
;             for (int st = 0; st < 3; ++st) { const int pi = (st & 1) ? 0 : 1, ti = st & 1;
;                 const int rt = (wid >> 1) & 1, ct = wid & 1; const f32x4 z4 = {0.f, 0.f, 0.f, 0.f};
;                 const int col = ct * 16 + r16, rb = rt * 16 + quad * 4;
;                 const bf16x8 yb = *(const LAS bf16x8*)(PTq[pi] + col * 40 + quad * 8);
;                 if (wid < 4) { const f32x4 acc = __builtin_amdgcn_mfma_f32_16x16x32_bf16(trfrag(PTq[pi], 40, 0, rt * 16, lane), yb, z4, 0, 0, 0);
;                     st_bf4(PTq[pi ^ 1] + col * 40 + rb, acc); }
;                 else { f32x4 acc = __builtin_amdgcn_mfma_f32_16x16x32_bf16(trfrag(Tq[ti], 40, 0, rt * 16, lane), yb, z4, 0, 0, 0);
;                     const u32x2 tw = *(const LAS u32x2*)(Tq[ti] + col * 40 + rb);
;                     acc[0] += bf_lo(tw.x); acc[1] += bf_hi(tw.x); acc[2] += bf_lo(tw.y); acc[3] += bf_hi(tw.y);
;                     st_bf4(Tq[ti ^ 1] + col * 40 + rb, acc); }
.LBB0_349:
	s_or_b64 exec, exec, s[24:25]
	s_waitcnt lgkmcnt(0)
	s_barrier
	s_waitcnt lgkmcnt(0)
	ds_read_b128 v[32:35], v36
	s_and_saveexec_b64 s[24:25], s[68:69]
	s_xor_b64 s[24:25], exec, s[24:25]
	s_cbranch_execz .LBB0_351
	ds_read_b64_tr_b16 v[36:37], v166
	ds_read_b64_tr_b16 v[38:39], v166 offset:320
	ds_read_b64 v[230:231], v167
	s_waitcnt lgkmcnt(0)
	v_mfma_f32_16x16x32_bf16 v[32:35], v[36:39], v[32:35], 0
	v_lshlrev_b32_e32 v38, 16, v230
	v_and_b32_e32 v39, 0xffff0000, v230
	v_lshlrev_b32_e32 v36, 16, v231
	v_and_b32_e32 v37, 0xffff0000, v231
	s_nop 3
	v_pk_add_f32 v[32:33], v[32:33], v[38:39]
	v_pk_add_f32 v[34:35], v[34:35], v[36:37]
	v_cvt_pk_bf16_f32 v32, v32, v33
	v_cvt_pk_bf16_f32 v33, v34, v35
	ds_write_b64 v179, v[32:33]

; #define LAS __attribute__((address_space(3)))
; __device__ __forceinline__ float bf_lo(unsigned w) { return __uint_as_float(w << 16); }
; __device__ __forceinline__ float bf_hi(unsigned w) { return __uint_as_float(w & 0xffff0000u); }
; __device__ __forceinline__ void st_bf4(LAS bf16_t* p, const f32x4 v) { u32x2 w; w.x = cvt_pk_bf16(v[0], v[1]); w.y = cvt_pk_bf16(v[2], v[3]); *(LAS u32x2*)p = w; }
; __device__ void rwkv_chunk_phase(const Params& p, int l, LAS unsigned char* lds) {
;     ...
;             if (wid < 4) { const int rt = wid >> 1, ct = wid & 1; const f32x4 z4 = {0.f, 0.f, 0.f, 0.f};
;                 const int col = ct * 16 + r16, rb = rt * 16 + quad * 4;
;                 f32x4 acc = __builtin_amdgcn_mfma_f32_16x16x32_bf16(trfrag(Tq[1], 40, 0, rt * 16, lane), *(const LAS bf16x8*)(PTq[0] + col * 40 + quad * 8), z4, 0, 0, 0);
;                 const u32x2 tw = *(const LAS u32x2*)(Tq[1] + col * 40 + rb);
;                 acc[0] += bf_lo(tw.x); acc[1] += bf_hi(tw.x); acc[2] += bf_lo(tw.y); acc[3] += bf_hi(tw.y);
;                 st_bf4(TT + col * 40 + rb, acc); }
.LBB0_353:
	s_or_b64 exec, exec, s[24:25]
	s_waitcnt lgkmcnt(0)
	s_barrier
	s_and_saveexec_b64 s[24:25], s[66:67]
	s_cbranch_execz .LBB0_355
	s_waitcnt lgkmcnt(0)
	ds_read_b64_tr_b16 v[32:33], v121
	ds_read_b64_tr_b16 v[34:35], v121 offset:320
	ds_read_b128 v[36:39], v3
	ds_read_b64 v[230:231], v122
	s_waitcnt lgkmcnt(0)
	v_mfma_f32_16x16x32_bf16 v[32:35], v[32:35], v[36:39], 0
	v_lshlrev_b32_e32 v38, 16, v230
	v_and_b32_e32 v39, 0xffff0000, v230
	v_lshlrev_b32_e32 v36, 16, v231
	v_and_b32_e32 v37, 0xffff0000, v231
	s_nop 3
	v_pk_add_f32 v[32:33], v[32:33], v[38:39]
	v_pk_add_f32 v[34:35], v[34:35], v[36:37]
	v_cvt_pk_bf16_f32 v32, v32, v33
	v_cvt_pk_bf16_f32 v33, v34, v35
	ds_write_b64 v123, v[32:33]
